# early acquire-invalidate: buffer_inv sc1 issued right after the arrive atomic so its latency overlaps the barrier wait (was after the wait); on top of v75
# speedup vs baseline: 1.0121x; 1.0093x over previous
.LBB0_42:
	v_readlane_b32 s2, v253, 2
	s_lshl_b32 s2, s2, 8
	s_add_u32 s2, s70, s2
	s_addc_u32 s3, s71, 0
	v_mov_b32_e32 v2, 0x1000
	v_mov_b32_e32 v4, 1
	global_atomic_add v4, v2, v4, s[2:3] offset:1024 sc0
	buffer_inv sc1
	s_waitcnt vmcnt(1) lgkmcnt(0)
	v_readfirstlane_b32 s2, v4
	v_readfirstlane_b32 s3, v3
	v_readfirstlane_b32 s8, v1
	s_mov_b32 s9, 0
	s_nop 1

.Lsb0_pl:
	global_load_dword v3, v2, s[44:45] offset:1024 sc1
	s_waitcnt vmcnt(0)
	v_readfirstlane_b32 s2, v3
	s_nop 1
	s_cmp_ge_u32 s2, s9
	s_cbranch_scc1 .Lsb0_pd
	s_add_u32 s8, s8, 1
	s_cmp_lt_u32 s8, 0x4000
	s_cbranch_scc0 .Lsb0_pd
	s_sleep 1
	s_branch .Lsb0_pl
.Lsb0_pd:
	s_waitcnt vmcnt(0)
.LBB0_74:
	s_or_b64 exec, exec, s[6:7]
	s_waitcnt lgkmcnt(0)
	s_barrier

.LBB0_129:
	v_readlane_b32 s2, v253, 2
	s_lshl_b32 s2, s2, 8
	v_readlane_b32 s6, v253, 21
	v_readlane_b32 s7, v253, 22
	s_add_u32 s2, s6, s2
	s_addc_u32 s3, s7, 0
	v_mov_b32_e32 v2, 0x1000
	v_mov_b32_e32 v4, 1
	global_atomic_add v4, v2, v4, s[2:3] offset:1024 sc0
	buffer_inv sc1
	s_waitcnt vmcnt(1) lgkmcnt(0)
	v_readfirstlane_b32 s2, v4
	v_readfirstlane_b32 s3, v3
	v_readfirstlane_b32 s8, v1
	s_mov_b32 s9, 0
	s_nop 1

.Lsb1_pl:
	global_load_dword v3, v2, s[44:45] offset:1024 sc1
	s_waitcnt vmcnt(0)
	v_readfirstlane_b32 s2, v3
	s_nop 1
	s_cmp_ge_u32 s2, s9
	s_cbranch_scc1 .Lsb1_pd
	s_add_u32 s8, s8, 1
	s_cmp_lt_u32 s8, 0x4000
	s_cbranch_scc0 .Lsb1_pd
	s_sleep 1
	s_branch .Lsb1_pl
.Lsb1_pd:
	s_waitcnt vmcnt(0)
.LBB0_161:
	s_or_b64 exec, exec, s[0:1]
	s_waitcnt lgkmcnt(0)
	s_barrier

.LBB0_723:
	v_readlane_b32 s2, v253, 2
	s_lshl_b32 s2, s2, 8
	s_add_u32 s2, s80, s2
	s_addc_u32 s3, s81, 0
	v_mov_b32_e32 v2, 0x1000
	v_mov_b32_e32 v4, 1
	global_atomic_add v4, v2, v4, s[2:3] offset:1024 sc0
	buffer_inv sc1
	s_waitcnt vmcnt(1) lgkmcnt(0)
	v_readfirstlane_b32 s2, v4
	v_readfirstlane_b32 s3, v3
	v_readfirstlane_b32 s8, v1
	s_mov_b32 s9, 0
	s_nop 1

.Lsb2_pl:
	global_load_dword v3, v2, s[44:45] offset:1024 sc1
	s_waitcnt vmcnt(0)
	v_readfirstlane_b32 s2, v3
	s_nop 1
	s_cmp_ge_u32 s2, s9
	s_cbranch_scc1 .Lsb2_pd
	s_add_u32 s8, s8, 1
	s_cmp_lt_u32 s8, 0x4000
	s_cbranch_scc0 .Lsb2_pd
	s_sleep 1
	s_branch .Lsb2_pl
.Lsb2_pd:
	s_waitcnt vmcnt(0)
.LBB0_755:
	s_or_b64 exec, exec, s[4:5]
	s_waitcnt lgkmcnt(0)
	s_barrier

.Lsb3_pl:
	global_load_dword v3, v2, s[44:45] offset:1024 sc1
	s_waitcnt vmcnt(0)
	v_readfirstlane_b32 s2, v3
	s_nop 1
	s_cmp_ge_u32 s2, s9
	s_cbranch_scc1 .Lsb3_pd
	s_add_u32 s8, s8, 1
	s_cmp_lt_u32 s8, 0x4000
	s_cbranch_scc0 .Lsb3_pd
	s_sleep 1
	s_branch .Lsb3_pl
.Lsb3_pd:
	s_waitcnt vmcnt(0)
.LBB0_923:
	s_or_b64 exec, exec, s[4:5]
	s_waitcnt lgkmcnt(0)
	s_barrier

.Lsb4_pl:
	global_load_dword v3, v2, s[44:45] offset:1024 sc1
	s_waitcnt vmcnt(0)
	v_readfirstlane_b32 s2, v3
	s_nop 1
	s_cmp_ge_u32 s2, s9
	s_cbranch_scc1 .Lsb4_pd
	s_add_u32 s8, s8, 1
	s_cmp_lt_u32 s8, 0x4000
	s_cbranch_scc0 .Lsb4_pd
	s_sleep 1
	s_branch .Lsb4_pl
.Lsb4_pd:
	s_waitcnt vmcnt(0)
.LBB0_1130:
	s_or_b64 exec, exec, s[4:5]
	s_waitcnt lgkmcnt(0)
	s_barrier

.Lsb5_pl:
	global_load_dword v3, v2, s[44:45] offset:1024 sc1
	s_waitcnt vmcnt(0)
	v_readfirstlane_b32 s2, v3
	s_nop 1
	s_cmp_ge_u32 s2, s9
	s_cbranch_scc1 .Lsb5_pd
	s_add_u32 s8, s8, 1
	s_cmp_lt_u32 s8, 0x4000
	s_cbranch_scc0 .Lsb5_pd
	s_sleep 1
	s_branch .Lsb5_pl
.Lsb5_pd:
	s_waitcnt vmcnt(0)
.LBB0_1224:
	s_or_b64 exec, exec, s[6:7]
	s_waitcnt lgkmcnt(0)
	s_barrier

.Lsb6_pl:
	global_load_dword v3, v2, s[44:45] offset:1024 sc1
	s_waitcnt vmcnt(0)
	v_readfirstlane_b32 s2, v3
	s_nop 1
	s_cmp_ge_u32 s2, s9
	s_cbranch_scc1 .Lsb6_pd
	s_add_u32 s8, s8, 1
	s_cmp_lt_u32 s8, 0x4000
	s_cbranch_scc0 .Lsb6_pd
	s_sleep 1
	s_branch .Lsb6_pl
.Lsb6_pd:
	s_waitcnt vmcnt(0)
.LBB0_1300:
	s_or_b64 exec, exec, s[0:1]
	s_waitcnt lgkmcnt(0)
	s_barrier
